# ret_out phase: nt hint on its last-use tile/Q/gate loads (P1, KVT, ST read once) + Relu2 canonicalize trim
# speedup vs baseline: 1.0137x; 1.0051x over previous
; #define LAS __attribute__((address_space(3)))
; #define R2_WRITE() do { _Pragma("unroll") for (int i = 0; i < 4; ++i) { const int idx = tid + NTHR * i, r = idx >> 4, c = idx & 15; \
;             *(LAS v4u*)(lS + r * PITCH + c * 16) = pS[i]; *(LAS v4u*)(lK + r * PITCH + c * 16) = pK[i]; *(LAS v4u*)(lV + r * PITCH + c * 16) = pV[i]; } } while (0)
; __device__ __forceinline__ void ret_out_phase(const bf16* P1, const bf16* KVT, const bf16* ST, const float* retg, bf16* Y, LAS unsigned char* lds, int bid, int G, int tid, int wave, int lane) {
;     constexpr int NU = BATCH * NHEAD * NCH, PITCH = 272, TILE = 128 * PITCH;
;     const int fr = lane & 15, fq = lane >> 4;
;     LAS unsigned char* lS = lds; LAS unsigned char* lK = lds + TILE; LAS unsigned char* lV = lds + 2 * TILE;
;     v4u pS[4], pK[4], pV[4]; bf16x8 qn[4]; v2u gn[8];
;     ...
;     int uc = 0, unit = bid;
;     const bool hfix = (G & 127) == 0;
;     f32x4 g4h[8];
;     { const float* gg0 = retg + ((bid >> 5) & 3) * 128 + 4 * fq;
; #pragma unroll
;       for (int te = 0; te < 8; ++te) g4h[te] = *(const f32x4*)(gg0 + 16 * te); }
;     if (unit < NU) { R2_ISSUE(unit, wave); R2_WRITE(); }
.LBB0_959:
	s_cmp_le_i32 s28, s8
	s_cselect_b64 s[2:3], -1, 0
	s_and_b64 s[0:1], s[2:3], s[0:1]
	s_andn2_b64 vcc, exec, s[0:1]
	s_cbranch_vccnz .LBB0_992
	s_mov_b32 s0, s10
	s_mov_b32 s8, s30
	v_mov_b32_e32 v82, v160
	v_mov_b32_e32 v0, s33
	ds_read_b64 v[0:1], v0
	v_readfirstlane_b32 s1, v82
	s_ashr_i32 s9, s1, 6
	v_readlane_b32 s1, v255, 8
	s_lshl_b32 s12, s62, 9
	v_and_b32_e32 v149, 48, v82
	v_mov_b32_e32 v2, s1
	ds_read_b64 v[2:3], v2
	s_waitcnt lgkmcnt(0)
	v_readfirstlane_b32 s4, v0
	v_readfirstlane_b32 s5, v1
	s_add_u32 s6, s4, 0xae00000
	s_addc_u32 s7, s5, 0
	s_add_u32 s2, s4, 0x16e00000
	s_addc_u32 s3, s5, 0
	s_add_u32 s66, s4, 0x1b300000
	s_addc_u32 s67, s5, 0
	v_readfirstlane_b32 s1, v2
	s_lshl_b64 s[16:17], s[12:13], 2
	v_readfirstlane_b32 s18, v3
	s_add_u32 s64, s1, s16
	s_addc_u32 s65, s18, s17
	s_lshl_b32 s1, s0, 2
	s_and_b32 s12, s1, 0x180
	s_lshl_b32 s1, s12, 2
	s_add_u32 s16, s64, s1
	s_addc_u32 s17, s65, 0
	global_load_dwordx4 v[0:3], v149, s[16:17] nt
	global_load_dwordx4 v[4:7], v149, s[16:17] offset:64 nt
	global_load_dwordx4 v[8:11], v149, s[16:17] offset:128 nt
	global_load_dwordx4 v[12:15], v149, s[16:17] offset:192 nt
	global_load_dwordx4 v[16:19], v149, s[16:17] offset:256 nt
	global_load_dwordx4 v[20:23], v149, s[16:17] offset:320 nt
	global_load_dwordx4 v[24:27], v149, s[16:17] offset:384 nt
	global_load_dwordx4 v[28:31], v149, s[16:17] offset:448 nt
	v_bfe_u32 v83, v82, 4, 2
	v_lshlrev_b32_e32 v84, 2, v83
	s_cmpk_lt_i32 s0, 0x400
	v_lshlrev_b32_e32 v32, 4, v82
	v_ashrrev_i32_e32 v150, 4, v82
	v_add_u32_e32 v33, 0x200, v82
	v_add_u32_e32 v34, 0x400, v82
	v_add_u32_e32 v35, 0x600, v82
	v_and_b32_e32 v148, 15, v82
	s_cselect_b64 s[68:69], -1, 0
	s_cmpk_gt_i32 s0, 0x3ff
	v_and_b32_e32 v80, 0xf0, v32
	v_lshlrev_b32_e32 v152, 7, v150
	v_ashrrev_i32_e32 v151, 31, v150
	v_ashrrev_i32_e32 v154, 4, v33
	v_ashrrev_i32_e32 v156, 4, v34
	v_ashrrev_i32_e32 v158, 4, v35
	v_lshlrev_b32_e32 v162, 1, v84
	v_mul_lo_u32 v175, v150, s49
	s_cbranch_scc1 .LBB0_962
; #define R2_WRITE() do { _Pragma("unroll") for (int i = 0; i < 4; ++i) { const int idx = tid + NTHR * i, r = idx >> 4, c = idx & 15; \
;             *(LAS v4u*)(lS + r * PITCH + c * 16) = pS[i]; *(LAS v4u*)(lK + r * PITCH + c * 16) = pK[i]; *(LAS v4u*)(lV + r * PITCH + c * 16) = pV[i]; } } while (0)
; __device__ __forceinline__ void ret_out_phase(const bf16* P1, const bf16* KVT, const bf16* ST, const float* retg, bf16* Y, LAS unsigned char* lds, int bid, int G, int tid, int wave, int lane) {
;     ...
;     if (unit < NU) { R2_ISSUE(unit, wave); R2_WRITE(); }
	s_ashr_i32 s16, s0, 7
	s_ashr_i32 s17, s16, 31
	s_lshl_b32 s1, s0, 7
	s_lshl_b64 s[70:71], s[16:17], 12
	s_and_b32 s1, s1, 0xf80
	s_or_b32 s70, s70, s1
	s_ashr_i32 s1, s0, 31
	s_lshl_b64 s[16:17], s[0:1], 15
	s_add_u32 s16, s66, s16
	s_addc_u32 s17, s67, s17
	v_mov_b32_e32 v81, v163
	v_lshl_add_u64 v[64:65], s[16:17], 0, v[80:81]
	s_or_b32 s1, s12, 0x200
	s_lshl_b64 s[16:17], s[70:71], 1
	s_add_u32 s16, s2, s16
	s_addc_u32 s17, s3, s17
	v_lshl_add_u64 v[34:35], s[70:71], 0, v[150:151]
	v_mov_b64_e32 v[86:87], s[6:7]
	v_ashrrev_i32_e32 v155, 31, v154
	v_ashrrev_i32_e32 v159, 31, v158
	v_lshl_add_u64 v[72:73], s[16:17], 0, v[80:81]
	v_mad_u64_u32 v[36:37], s[16:17], v34, s47, v[86:87]
	v_lshl_add_u64 v[48:49], s[70:71], 0, v[154:155]
	v_lshl_add_u64 v[74:75], s[70:71], 0, v[158:159]
	v_mad_i32_i24 v37, v35, s47, v37
	s_lshl_b32 s12, s12, 1
	v_mad_u64_u32 v[50:51], s[16:17], v48, s47, v[86:87]
	v_mad_u64_u32 v[76:77], s[16:17], v74, s47, v[86:87]
	v_lshl_add_u64 v[34:35], v[36:37], 0, s[12:13]
	v_mad_i32_i24 v51, v49, s47, v51
	v_ashrrev_i32_e32 v157, 31, v156
	v_mad_i32_i24 v77, v75, s47, v77
	v_lshl_add_u64 v[34:35], v[34:35], 0, v[80:81]
	v_add_u32_e32 v40, s1, v150
	v_lshl_add_u64 v[48:49], v[50:51], 0, s[12:13]
	v_add_u32_e32 v50, s1, v154
	v_lshl_add_u64 v[58:59], s[70:71], 0, v[156:157]
	v_add_u32_e32 v66, s1, v156
	v_lshl_add_u64 v[74:75], v[76:77], 0, s[12:13]
	v_add_u32_e32 v76, s1, v158
	v_add_co_u32_e32 v36, vcc, s46, v34
	v_mad_i64_i32 v[40:41], s[16:17], v40, s45, v[72:73]
	v_mad_i64_i32 v[50:51], s[16:17], v50, s45, v[72:73]
	v_mad_u64_u32 v[60:61], s[16:17], v58, s47, v[86:87]
	v_mad_i64_i32 v[66:67], s[16:17], v66, s45, v[72:73]
	v_mad_i64_i32 v[72:73], s[16:17], v76, s45, v[72:73]
	s_lshl_b32 s1, s9, 4
	v_addc_co_u32_e32 v37, vcc, 0, v35, vcc
	v_lshl_add_u64 v[48:49], v[48:49], 0, v[80:81]
	v_mad_i32_i24 v61, v59, s47, v61
	s_ashr_i32 s16, s1, 31
	v_add_co_u32_e32 v48, vcc, s46, v48
	v_lshl_add_u64 v[58:59], v[60:61], 0, s[12:13]
	s_add_u32 s1, s70, s1
	v_addc_co_u32_e32 v49, vcc, 0, v49, vcc
	v_lshl_add_u64 v[58:59], v[58:59], 0, v[80:81]
	v_lshl_add_u64 v[74:75], v[74:75], 0, v[80:81]
	v_or_b32_e32 v81, s1, v148
	v_add_co_u32_e32 v60, vcc, s46, v58
	s_addc_u32 s18, s71, s16
	v_mad_u64_u32 v[86:87], s[16:17], v81, s47, v[86:87]
	v_ashrrev_i32_e32 v153, 31, v152
	v_lshlrev_b32_e32 v42, 7, v154
	v_lshlrev_b32_e32 v56, 7, v156
	v_addc_co_u32_e32 v61, vcc, 0, v59, vcc
	v_lshlrev_b32_e32 v68, 7, v158
	v_mad_i32_i24 v87, s18, v229, v87
	v_lshl_add_u64 v[32:33], v[152:153], 1, v[64:65]
	v_ashrrev_i32_e32 v43, 31, v42
	v_ashrrev_i32_e32 v57, 31, v56
	v_ashrrev_i32_e32 v69, 31, v68
	v_add_co_u32_e32 v74, vcc, s46, v74
	v_lshl_add_u64 v[86:87], v[86:87], 0, s[12:13]
	v_lshlrev_b32_e32 v88, 4, v83
	v_mov_b32_e32 v89, v163
	global_load_dwordx4 v[32:35], v[32:33], off nt
	s_nop 0
	global_load_dwordx4 v[36:39], v[36:37], off nt
	v_lshl_add_u64 v[44:45], v[42:43], 1, v[64:65]
	v_lshl_add_u64 v[56:57], v[56:57], 1, v[64:65]
	v_lshl_add_u64 v[68:69], v[68:69], 1, v[64:65]
	v_addc_co_u32_e32 v75, vcc, 0, v75, vcc
	v_lshl_add_u64 v[88:89], v[86:87], 0, v[88:89]
	v_lshl_add_u64 v[86:87], v[86:87], 0, v[162:163]
	global_load_dwordx4 v[40:43], v[40:41], off nt
	s_nop 0
	global_load_dwordx4 v[44:47], v[44:45], off nt
	s_nop 0
	global_load_dwordx4 v[52:55], v[48:49], off nt
	s_nop 0
	global_load_dwordx4 v[48:51], v[50:51], off nt
	s_nop 0
	global_load_dwordx4 v[56:59], v[56:57], off nt
	s_nop 0
	global_load_dwordx4 v[60:63], v[60:61], off nt
	s_nop 0
	global_load_dwordx4 v[64:67], v[66:67], off nt
	s_nop 0
	global_load_dwordx4 v[68:71], v[68:69], off nt
	s_nop 0
	global_load_dwordx4 v[76:79], v[74:75], off nt
	s_nop 0
	global_load_dwordx4 v[72:75], v[72:73], off nt
	s_nop 0
	global_load_dwordx4 v[132:135], v[88:89], off offset:3072 nt
	global_load_dwordx4 v[128:131], v[88:89], off offset:3136 nt
	global_load_dwordx4 v[124:127], v[88:89], off offset:3200 nt
	global_load_dwordx4 v[120:123], v[88:89], off offset:3264 nt
	v_lshl_add_u64 v[88:89], v[86:87], 0, s[90:91]
	v_add_co_u32_e32 v86, vcc, s46, v86
	v_add_u32_e32 v81, 0, v80
	s_nop 0
	v_addc_co_u32_e32 v87, vcc, 0, v87, vcc
	global_load_dwordx2 v[214:215], v[88:89], off offset:32 nt
	global_load_dwordx2 v[212:213], v[88:89], off offset:64 nt
	global_load_dwordx2 v[210:211], v[88:89], off offset:96 nt
	global_load_dwordx2 v[208:209], v[88:89], off offset:128 nt
	global_load_dwordx2 v[216:217], v[86:87], off offset:1024 nt
	global_load_dwordx2 v[206:207], v[88:89], off offset:160 nt
	global_load_dwordx2 v[204:205], v[88:89], off offset:192 nt
	global_load_dwordx2 v[186:187], v[88:89], off offset:224 nt
	v_add_u32_e32 v85, s48, v80
	v_add_u32_e32 v86, v81, v175
	s_waitcnt vmcnt(0)
	ds_write_b128 v86, v[32:35]
	ds_write_b128 v86, v[36:39] offset:34816
	v_add_u32_e32 v86, v85, v175
	ds_write_b128 v86, v[40:43]
	v_mul_lo_u32 v86, v154, s49
	v_add_u32_e32 v87, v81, v86
	v_add_u32_e32 v86, v85, v86
	ds_write_b128 v87, v[44:47]
	ds_write_b128 v87, v[52:55] offset:34816
	ds_write_b128 v86, v[48:51]
	v_mul_lo_u32 v86, v156, s49
	v_add_u32_e32 v87, v81, v86
	v_add_u32_e32 v86, v85, v86
	ds_write_b128 v87, v[56:59]
	ds_write_b128 v87, v[60:63] offset:34816
	ds_write_b128 v86, v[64:67]
	v_mul_lo_u32 v86, v158, s49
	v_add_u32_e32 v81, v81, v86
	ds_write_b128 v81, v[68:71]
	ds_write_b128 v81, v[76:79] offset:34816
	v_add_u32_e32 v81, v85, v86
	ds_write_b128 v81, v[72:75]

; __device__ __forceinline__ void ret_out_phase(const bf16* P1, const bf16* KVT, const bf16* ST, const float* retg, bf16* Y, LAS unsigned char* lds, int bid, int G, int tid, int wave, int lane) {
;     ...
;         const int nxt = unit + G; const bool has = nxt < NU;
;         if (has) { const int wn = ((uc + 1) & 1) ? 7 - wave : wave; R2_ISSUE(nxt, wn); }
.LBB0_965:
	s_bitcmp0_b32 s16, 0
	s_cselect_b64 s[2:3], -1, 0
	s_add_i32 s66, s0, s8
	s_cmpk_lt_i32 s66, 0x400
	s_cselect_b64 s[70:71], -1, 0
	s_cmpk_gt_i32 s66, 0x3ff
	s_cselect_b64 s[68:69], -1, 0
	s_and_b64 vcc, exec, s[68:69]
	s_cbranch_vccnz .LBB0_967
	s_ashr_i32 s18, s66, 7
	s_ashr_i32 s19, s18, 31
	s_lshl_b32 s1, s66, 7
	s_lshl_b64 s[72:73], s[18:19], 12
	s_and_b32 s1, s1, 0xf80
	s_or_b32 s72, s72, s1
	s_ashr_i32 s67, s66, 31
	s_lshl_b64 s[18:19], s[66:67], 15
	s_lshl_b32 s1, s66, 2
	v_lshl_add_u64 v[34:35], s[72:73], 0, v[150:151]
	v_mov_b64_e32 v[80:81], s[6:7]
	v_lshl_add_u64 v[64:65], v[170:171], 0, s[18:19]
	s_and_b32 s1, s1, 0x180
	v_mad_u64_u32 v[36:37], s[18:19], v34, s47, v[80:81]
	v_lshl_add_u64 v[48:49], s[72:73], 0, v[154:155]
	v_lshl_add_u64 v[74:75], s[72:73], 0, v[158:159]
	s_or_b32 s20, s1, 0x200
	v_mad_i32_i24 v37, v35, s47, v37
	s_lshl_b32 s12, s1, 1
	v_mad_u64_u32 v[50:51], s[18:19], v48, s47, v[80:81]
	v_mad_u64_u32 v[76:77], s[18:19], v74, s47, v[80:81]
	v_lshl_add_u64 v[34:35], v[36:37], 0, s[12:13]
	v_mov_b32_e32 v185, v163
	v_mad_i32_i24 v51, v49, s47, v51
	v_mad_i32_i24 v77, v75, s47, v77
	s_and_b64 s[18:19], s[2:3], exec
	v_lshl_add_u64 v[72:73], s[72:73], 1, v[172:173]
	v_lshl_add_u64 v[34:35], v[34:35], 0, v[184:185]
	v_add_u32_e32 v40, s20, v150
	v_lshl_add_u64 v[48:49], v[50:51], 0, s[12:13]
	v_add_u32_e32 v50, s20, v154
	v_lshl_add_u64 v[58:59], s[72:73], 0, v[156:157]
	v_add_u32_e32 v66, s20, v156
	v_lshl_add_u64 v[74:75], v[76:77], 0, s[12:13]
	v_add_u32_e32 v76, s20, v158
	s_cselect_b32 s1, s17, s9
	v_add_co_u32_e32 v36, vcc, s46, v34
	v_mad_i64_i32 v[40:41], s[18:19], v40, s45, v[72:73]
	v_mad_i64_i32 v[50:51], s[18:19], v50, s45, v[72:73]
	v_mad_u64_u32 v[60:61], s[18:19], v58, s47, v[80:81]
	v_mad_i64_i32 v[66:67], s[18:19], v66, s45, v[72:73]
	v_mad_i64_i32 v[72:73], s[18:19], v76, s45, v[72:73]
	s_lshl_b32 s1, s1, 4
	v_addc_co_u32_e32 v37, vcc, 0, v35, vcc
	v_lshl_add_u64 v[48:49], v[48:49], 0, v[184:185]
	v_mad_i32_i24 v61, v59, s47, v61
	s_ashr_i32 s18, s1, 31
	v_add_co_u32_e32 v48, vcc, s46, v48
	v_lshl_add_u64 v[58:59], v[60:61], 0, s[12:13]
	s_add_u32 s1, s72, s1
	v_addc_co_u32_e32 v49, vcc, 0, v49, vcc
	v_lshl_add_u64 v[58:59], v[58:59], 0, v[184:185]
	v_or_b32_e32 v82, s1, v148
	v_add_co_u32_e32 v60, vcc, s46, v58
	s_addc_u32 s20, s73, s18
	v_mad_u64_u32 v[80:81], s[18:19], v82, s47, v[80:81]
	v_addc_co_u32_e32 v61, vcc, 0, v59, vcc
	v_lshl_add_u64 v[74:75], v[74:75], 0, v[184:185]
	v_mad_i32_i24 v81, s20, v229, v81
	v_add_co_u32_e32 v74, vcc, s46, v74
	v_lshl_add_u64 v[96:97], v[80:81], 0, s[12:13]
	v_lshlrev_b32_e32 v80, 1, v174
	v_mov_b32_e32 v81, v163
	v_addc_co_u32_e32 v75, vcc, 0, v75, vcc
	v_lshl_add_u64 v[92:93], v[96:97], 0, v[80:81]
	v_lshl_add_u64 v[96:97], v[96:97], 0, v[162:163]
	v_lshl_add_u64 v[32:33], v[152:153], 1, v[64:65]
	v_lshl_add_u64 v[44:45], v[178:179], 1, v[64:65]
	v_lshl_add_u64 v[56:57], v[180:181], 1, v[64:65]
	v_lshl_add_u64 v[68:69], v[182:183], 1, v[64:65]
	v_lshl_add_u64 v[98:99], v[96:97], 0, s[90:91]
	v_add_co_u32_e32 v96, vcc, 0x1000, v96
	global_load_dwordx4 v[32:35], v[32:33], off nt
	s_nop 0
	global_load_dwordx4 v[36:39], v[36:37], off nt
	s_nop 0
	global_load_dwordx4 v[40:43], v[40:41], off nt
	s_nop 0
	global_load_dwordx4 v[44:47], v[44:45], off nt
	s_nop 0
	global_load_dwordx4 v[52:55], v[48:49], off nt
	s_nop 0
	global_load_dwordx4 v[48:51], v[50:51], off nt
	s_nop 0
	global_load_dwordx4 v[56:59], v[56:57], off nt
	s_nop 0
	global_load_dwordx4 v[60:63], v[60:61], off nt
	s_nop 0
	global_load_dwordx4 v[64:67], v[66:67], off nt
	s_nop 0
	global_load_dwordx4 v[68:71], v[68:69], off nt
	s_nop 0
	global_load_dwordx4 v[76:79], v[74:75], off nt
	s_nop 0
	global_load_dwordx4 v[72:75], v[72:73], off nt
	s_nop 0
	global_load_dwordx4 v[80:83], v[92:93], off offset:3072 nt
	global_load_dwordx4 v[84:87], v[92:93], off offset:3136 nt
	global_load_dwordx4 v[88:91], v[92:93], off offset:3200 nt
	s_nop 0
	global_load_dwordx4 v[92:95], v[92:93], off offset:3264 nt
	v_addc_co_u32_e32 v97, vcc, 0, v97, vcc
	global_load_dwordx2 v[192:193], v[98:99], off offset:32 nt
	global_load_dwordx2 v[190:191], v[98:99], off offset:64 nt
	global_load_dwordx2 v[188:189], v[98:99], off offset:96 nt
	global_load_dwordx2 v[196:197], v[98:99], off offset:128 nt
	global_load_dwordx2 v[194:195], v[96:97], off offset:1024 nt
	global_load_dwordx2 v[198:199], v[98:99], off offset:160 nt
	global_load_dwordx2 v[200:201], v[98:99], off offset:192 nt
	global_load_dwordx2 v[202:203], v[98:99], off offset:224 nt

; __device__ __forceinline__ void ret_out_phase(const bf16* P1, const bf16* KVT, const bf16* ST, const float* retg, bf16* Y, LAS unsigned char* lds, int bid, int G, int tid, int wave, int lane) {
;     ...
;         float s = 0.f;
; #pragma unroll
;         for (int te = 0; te < 8; ++te) s += (o[te][0] + o[te][1]) + (o[te][2] + o[te][3]);
;         s += __shfl_xor(s, 16); s += __shfl_xor(s, 32);
;         const float mean = s * (1.f / 128.f); float q = 0.f;
; #pragma unroll
;         for (int te = 0; te < 8; ++te) { const f32x4 dlt = o[te] - mean; q += (dlt[0] * dlt[0] + dlt[1] * dlt[1]) + (dlt[2] * dlt[2] + dlt[3] * dlt[3]); }
;         q += __shfl_xor(q, 16); q += __shfl_xor(q, 32);
;     ...
;             const v2u gw2 = gq[te]; const f32x4 g4 = hfix ? g4h[te] : *(const f32x4*)(gg + 16 * te);
.LBB0_974:
	v_mov_b32_e32 v120, v112
	v_mov_b32_e32 v121, v116
	v_mov_b32_e32 v122, v113
	v_mov_b32_e32 v123, v117
	v_pk_add_f32 v[120:121], v[120:121], v[122:123]
	v_mov_b32_e32 v122, v114
	v_mov_b32_e32 v123, v118
	v_mov_b32_e32 v124, v115
	v_mov_b32_e32 v125, v119
	v_pk_add_f32 v[122:123], v[122:123], v[124:125]
	v_mov_b32_e32 v124, v108
	v_pk_add_f32 v[120:121], v[120:121], v[122:123]
	v_mov_b32_e32 v122, v109
	v_mov_b32_e32 v123, v110
	v_mov_b32_e32 v125, v111
	v_pk_add_f32 v[122:123], v[122:123], v[124:125]
	v_add_f32_e32 v121, 0, v121
	v_pk_add_f32 v[122:123], v[122:123], v[122:123] op_sel_hi:[0,1]
	v_add_f32_e32 v121, v120, v121
	v_add_f32_e32 v125, v104, v105
	v_add_f32_e32 v127, v106, v107
	v_mov_b32_e32 v124, v136
	v_mov_b32_e32 v126, v137
	v_mov_b32_e32 v122, v138
	v_mov_b32_e32 v120, v139
	v_pk_add_f32 v[124:125], v[124:125], v[126:127]
	v_pk_add_f32 v[120:121], v[122:123], v[120:121]
	v_mov_b32_e32 v122, v101
	v_pk_add_f32 v[120:121], v[124:125], v[120:121]
	v_mov_b32_e32 v123, v102
	v_mov_b32_e32 v124, v100
	v_mov_b32_e32 v125, v103
	v_pk_add_f32 v[122:123], v[122:123], v[124:125]
	v_pk_add_f32 v[120:121], v[120:121], v[120:121] op_sel_hi:[0,1]
	v_pk_add_f32 v[122:123], v[122:123], v[122:123] op_sel_hi:[0,1]
	v_add_f32_e32 v125, v96, v97
	v_add_f32_e32 v127, v98, v99
	v_mov_b32_e32 v124, v140
	v_mov_b32_e32 v126, v141
	v_mov_b32_e32 v122, v142
	v_mov_b32_e32 v120, v143
	v_pk_add_f32 v[124:125], v[124:125], v[126:127]
	v_pk_add_f32 v[120:121], v[122:123], v[120:121]
	v_mov_b32_e32 v144, v137
	v_pk_add_f32 v[120:121], v[124:125], v[120:121]
	s_lshl_b32 s1, s0, 2
	v_add_f32_e32 v120, v120, v121
	ds_bpermute_b32 v121, v231, v120
	s_and_b32 s3, s1, 0x180
	s_lshl_b32 s12, s3, 2
	v_mov_b32_e32 v134, v136
	v_mov_b32_e32 v135, v138
	s_waitcnt lgkmcnt(0)
	v_add_f32_e32 v120, v120, v121
	ds_bpermute_b32 v121, v232, v120
	v_mov_b32_e32 v145, v139
	v_mov_b32_e32 v128, v140
	v_mov_b32_e32 v129, v142
	v_mov_b32_e32 v127, v143
	s_waitcnt lgkmcnt(0)
	v_add_f32_e32 v124, v120, v121
	v_fmamk_f32 v121, v124, 0xbc000000, v119
	v_fmamk_f32 v123, v124, 0xbc000000, v117
	v_fmamk_f32 v120, v124, 0xbc000000, v118
	v_fmamk_f32 v122, v124, 0xbc000000, v116
	v_mul_f32_e32 v123, v123, v123
	v_mul_f32_e32 v121, v121, v121
	v_fmac_f32_e32 v123, v122, v122
	v_fmac_f32_e32 v121, v120, v120
	v_fmamk_f32 v122, v124, 0xbc000000, v115
	v_fmamk_f32 v125, v124, 0xbc000000, v113
	v_add_f32_e32 v120, v123, v121
	v_fmamk_f32 v121, v124, 0xbc000000, v114
	v_fmamk_f32 v123, v124, 0xbc000000, v112
	v_mul_f32_e32 v125, v125, v125
	v_mul_f32_e32 v122, v122, v122
	v_fmac_f32_e32 v125, v123, v123
	v_fmac_f32_e32 v122, v121, v121
	v_add_f32_e32 v121, v125, v122
	v_fmamk_f32 v122, v124, 0xbc000000, v111
	v_fmamk_f32 v125, v124, 0xbc000000, v109
	v_add_f32_e32 v120, v120, v121
	v_fmamk_f32 v121, v124, 0xbc000000, v110
	v_fmamk_f32 v123, v124, 0xbc000000, v108
	v_mul_f32_e32 v125, v125, v125
	v_mul_f32_e32 v122, v122, v122
	v_fmac_f32_e32 v125, v123, v123
	v_fmac_f32_e32 v122, v121, v121
	v_add_f32_e32 v121, v125, v122
	v_fmamk_f32 v122, v124, 0xbc000000, v107
	v_fmamk_f32 v125, v124, 0xbc000000, v105
	v_add_f32_e32 v120, v121, v120
	v_fmamk_f32 v121, v124, 0xbc000000, v106
	v_fmamk_f32 v123, v124, 0xbc000000, v104
	v_mul_f32_e32 v125, v125, v125
	v_mul_f32_e32 v122, v122, v122
	v_fmac_f32_e32 v125, v123, v123
	v_fmac_f32_e32 v122, v121, v121
	v_add_f32_e32 v121, v125, v122
	v_fmamk_f32 v122, v124, 0xbc000000, v139
	v_fmac_f32_e32 v137, 0xbc000000, v124
	v_add_f32_e32 v120, v121, v120
	v_fmamk_f32 v121, v124, 0xbc000000, v138
	v_fmamk_f32 v123, v124, 0xbc000000, v136
	v_mul_f32_e32 v125, v137, v137
	v_mul_f32_e32 v122, v122, v122
	v_fmac_f32_e32 v125, v123, v123
	v_fmac_f32_e32 v122, v121, v121
	v_add_f32_e32 v121, v125, v122
	v_fmamk_f32 v122, v124, 0xbc000000, v103
	v_fmamk_f32 v125, v124, 0xbc000000, v101
	v_add_f32_e32 v120, v121, v120
	v_fmamk_f32 v121, v124, 0xbc000000, v102
	v_fmamk_f32 v123, v124, 0xbc000000, v100
	v_mul_f32_e32 v125, v125, v125
	v_mul_f32_e32 v122, v122, v122
	v_fmac_f32_e32 v125, v123, v123
	v_fmac_f32_e32 v122, v121, v121
	v_add_f32_e32 v121, v125, v122
	v_fmamk_f32 v122, v124, 0xbc000000, v99
	v_fmamk_f32 v125, v124, 0xbc000000, v97
	v_add_f32_e32 v120, v121, v120
	v_fmamk_f32 v121, v124, 0xbc000000, v98
	v_fmamk_f32 v123, v124, 0xbc000000, v96
	v_mul_f32_e32 v125, v125, v125
	v_mul_f32_e32 v122, v122, v122
	v_fmac_f32_e32 v125, v123, v123
	v_fmac_f32_e32 v122, v121, v121
	v_add_f32_e32 v121, v125, v122
	v_fmamk_f32 v122, v124, 0xbc000000, v143
	v_fmac_f32_e32 v141, 0xbc000000, v124
	v_add_f32_e32 v120, v121, v120
	v_fmamk_f32 v121, v124, 0xbc000000, v142
	v_fmamk_f32 v123, v124, 0xbc000000, v140
	v_mul_f32_e32 v125, v141, v141
	v_mul_f32_e32 v122, v122, v122
	v_fmac_f32_e32 v125, v123, v123
	v_fmac_f32_e32 v122, v121, v121
	v_add_f32_e32 v121, v125, v122
	v_add_f32_e32 v120, v121, v120
	ds_bpermute_b32 v121, v231, v120
	v_lshl_add_u64 v[130:131], v[168:169], 0, s[12:13]
	s_and_b64 vcc, exec, s[64:65]
	s_waitcnt lgkmcnt(0)
	v_add_f32_e32 v125, v120, v121
	ds_bpermute_b32 v133, v232, v125
	v_mov_b64_e32 v[122:123], v[2:3]
	v_mov_b64_e32 v[120:121], v[0:1]
	s_cbranch_vccz .LBB0_976
	global_load_dwordx4 v[120:123], v[130:131], off nt
; __device__ __forceinline__ unsigned pk2(float lo, float hi) { return f2bf(lo) | (f2bf(hi) << 16); }
; __device__ __forceinline__ void ret_out_phase(const bf16* P1, const bf16* KVT, const bf16* ST, const float* retg, bf16* Y, LAS unsigned char* lds, int bid, int G, int tid, int wave, int lane) {
;     ...
;         const float rstd = 1.f / sqrtf(q * (1.f / 128.f) + EPS);
;         bf16* yrow = Y + (tok0 + 16 * w + fr) * D + 512 + h * 128 + 4 * fq;
;         const float* gg = retg + h * 128 + 4 * fq;
; #pragma unroll
;         for (int te = 0; te < 8; ++te) {
;             const v2u gw2 = gq[te]; const f32x4 g4 = hfix ? g4h[te] : *(const f32x4*)(gg + 16 * te);
;             float gv[4] = {bflo(gw2.x), bfhi(gw2.x), bflo(gw2.y), bfhi(gw2.y)}; float y[4];
; #pragma unroll
;             for (int r = 0; r < 4; ++r) { const float sl = gv[r] / (1.f + __expf(-gv[r])); y[r] = (o[te][r] - mean) * rstd * g4[r] * sl; }
;             v2u ov; ov.x = pk2(y[0], y[1]); ov.y = pk2(y[2], y[3]);
;             *(v2u*)(yrow + 16 * te) = ov;
.LBB0_976:
	v_mul_f32_e32 v132, 0x3c000000, v124
	s_waitcnt lgkmcnt(0)
	v_add_f32_e32 v124, v125, v133
	v_fmamk_f32 v124, v124, 0x3c000000, v161
	v_cmp_gt_f32_e32 vcc, s58, v124
	v_mul_f32_e32 v125, 0x4f800000, v124
	s_ashr_i32 s18, s0, 7
	v_cndmask_b32_e32 v124, v124, v125, vcc
	v_sqrt_f32_e32 v125, v124
	s_ashr_i32 s19, s18, 31
	s_lshl_b32 s0, s0, 7
	s_and_b32 s0, s0, 0xf80
	v_add_u32_e32 v133, -1, v125
	s_lshl_b64 s[18:19], s[18:19], 12
	v_fma_f32 v136, -v133, v125, v124
	s_or_b32 s12, s18, s0
	v_cmp_ge_f32_e64 s[0:1], 0, v136
	v_add_u32_e32 v136, 1, v125
	v_mov_b32_e32 v139, v118
	v_cndmask_b32_e64 v133, v125, v133, s[0:1]
	v_fma_f32 v125, -v136, v125, v124
	v_cmp_lt_f32_e64 s[0:1], 0, v125
	v_mov_b32_e32 v118, v117
	v_and_b32_e32 v147, 0xffff0000, v216
	v_cndmask_b32_e64 v125, v133, v136, s[0:1]
	v_mul_f32_e32 v133, 0x37800000, v125
	v_cndmask_b32_e32 v125, v125, v133, vcc
	v_cmp_class_f32_e32 vcc, v124, v177
	v_and_b32_e32 v146, 0xffff0000, v217
	s_nop 0
	v_cndmask_b32_e32 v124, v125, v124, vcc
	v_div_scale_f32 v125, s[0:1], v124, v124, 1.0
	v_rcp_f32_e32 v133, v125
	s_ashr_i32 s0, s2, 31
	s_add_u32 s1, s12, s2
	s_addc_u32 s0, s19, s0
	v_fma_f32 v136, -v125, v133, 1.0
	v_fmac_f32_e32 v133, v136, v133
	v_div_scale_f32 v136, vcc, 1.0, v124, 1.0
	v_mul_f32_e32 v137, v136, v133
	v_fma_f32 v138, -v125, v137, v136
	v_fmac_f32_e32 v137, v138, v133
	v_fma_f32 v125, -v125, v137, v136
	v_div_fmas_f32 v125, v125, v133, v137
	v_mov_b32_e32 v138, v116
	v_div_fixup_f32 v124, v125, v124, 1.0
	v_pk_add_f32 v[138:139], v[138:139], v[132:133] op_sel_hi:[1,0] neg_lo:[0,1] neg_hi:[0,1]
	v_pk_add_f32 v[116:117], v[118:119], v[132:133] op_sel_hi:[1,0] neg_lo:[0,1] neg_hi:[0,1]
	v_lshlrev_b32_e32 v125, 16, v217
	v_lshlrev_b32_e32 v133, 16, v216
	v_mul_f32_e32 v119, 0xbfb8aa3b, v147
	v_mul_f32_e32 v118, 0xbfb8aa3b, v133
	v_exp_f32_e32 v140, v119
	v_mul_f32_e32 v119, 0xbfb8aa3b, v125
	v_exp_f32_e32 v118, v118
	v_exp_f32_e32 v119, v119
	v_mov_b32_e32 v137, s0
	v_or_b32_e32 v136, s1, v148
	v_lshlrev_b64 v[136:137], 11, v[136:137]
	v_pk_add_f32 v[118:119], v[118:119], 1.0 op_sel_hi:[1,0]
	v_lshl_add_u64 v[136:137], s[4:5], 0, v[136:137]
	v_div_scale_f32 v141, s[0:1], v119, v119, v125
	v_rcp_f32_e32 v142, v141
	s_lshl_b32 s12, s3, 1
	v_lshl_add_u64 v[136:137], v[136:137], 0, s[12:13]
	v_lshl_add_u64 v[136:137], v[136:137], 0, v[162:163]
	v_fma_f32 v143, -v141, v142, 1.0
	v_fmac_f32_e32 v142, v143, v142
	v_div_scale_f32 v143, vcc, v125, v119, v125
	v_mul_f32_e32 v185, v143, v142
	v_fma_f32 v216, -v141, v185, v143
	v_fmac_f32_e32 v185, v216, v142
	v_fma_f32 v141, -v141, v185, v143
	v_div_fmas_f32 v141, v141, v142, v185
	v_div_fixup_f32 v119, v141, v119, v125
	v_div_scale_f32 v125, s[0:1], v118, v118, v133
	v_rcp_f32_e32 v141, v125
	s_nop 0
	v_fma_f32 v142, -v125, v141, 1.0
	v_fmac_f32_e32 v141, v142, v141
	v_div_scale_f32 v142, vcc, v133, v118, v133
	v_mul_f32_e32 v143, v142, v141
	v_fma_f32 v185, -v125, v143, v142
	v_fmac_f32_e32 v143, v185, v141
	v_fma_f32 v125, -v125, v143, v142
	s_waitcnt vmcnt(0)
	v_mov_b32_e32 v142, v120
	v_mul_f32_e32 v120, 0xbfb8aa3b, v146
	v_div_fmas_f32 v125, v125, v141, v143
	v_exp_f32_e32 v141, v120
	v_pk_mul_f32 v[138:139], v[138:139], v[124:125] op_sel_hi:[1,0]
	v_mov_b32_e32 v143, v122
	v_div_fixup_f32 v118, v125, v118, v133
	v_pk_mul_f32 v[138:139], v[138:139], v[142:143]
	s_nop 0
	v_pk_mul_f32 v[118:119], v[118:119], v[138:139]
	v_pk_add_f32 v[138:139], v[140:141], 1.0 op_sel_hi:[1,0]
	s_nop 0
	v_div_scale_f32 v120, s[0:1], v139, v139, v146
	v_rcp_f32_e32 v122, v120
	s_nop 0
	v_fma_f32 v125, -v120, v122, 1.0
	v_fmac_f32_e32 v122, v125, v122
	v_div_scale_f32 v125, vcc, v146, v139, v146
	v_mul_f32_e32 v133, v125, v122
	v_fma_f32 v140, -v120, v133, v125
	v_fmac_f32_e32 v133, v140, v122
	v_fma_f32 v120, -v120, v133, v125
	v_div_fmas_f32 v120, v120, v122, v133
	v_div_fixup_f32 v139, v120, v139, v146
	v_div_scale_f32 v120, s[0:1], v138, v138, v147
	v_rcp_f32_e32 v122, v120
	s_nop 0
	v_fma_f32 v125, -v120, v122, 1.0
	v_fmac_f32_e32 v122, v125, v122
	v_div_scale_f32 v125, vcc, v147, v138, v147
	v_mul_f32_e32 v133, v125, v122
	v_fma_f32 v140, -v120, v133, v125
	v_fmac_f32_e32 v133, v140, v122
	v_fma_f32 v120, -v120, v133, v125
	v_div_fmas_f32 v120, v120, v122, v133
	v_pk_mul_f32 v[116:117], v[116:117], v[124:125] op_sel_hi:[1,0]
	v_mov_b32_e32 v122, v121
	v_div_fixup_f32 v138, v120, v138, v147
	v_pk_mul_f32 v[116:117], v[116:117], v[122:123]
	v_and_b32_sdwa v121, v118, v220 dst_sel:DWORD dst_unused:UNUSED_PAD src0_sel:WORD_1 src1_sel:DWORD
	v_pk_mul_f32 v[116:117], v[138:139], v[116:117]
	v_and_b32_sdwa v120, v119, v220 dst_sel:DWORD dst_unused:UNUSED_PAD src0_sel:WORD_1 src1_sel:DWORD
	v_add3_u32 v118, v118, v121, s59
	v_and_b32_sdwa v121, v116, v220 dst_sel:DWORD dst_unused:UNUSED_PAD src0_sel:WORD_1 src1_sel:DWORD
	v_add3_u32 v119, v119, v120, s59
	v_and_b32_sdwa v120, v117, v220 dst_sel:DWORD dst_unused:UNUSED_PAD src0_sel:WORD_1 src1_sel:DWORD
	v_add3_u32 v116, v116, v121, s59
	v_add3_u32 v117, v117, v120, s59
	v_and_b32_e32 v116, 0xffff0000, v116
	v_and_b32_e32 v117, 0xffff0000, v117
	v_or_b32_sdwa v116, v116, v118 dst_sel:DWORD dst_unused:UNUSED_PAD src0_sel:DWORD src1_sel:WORD_1
	v_add_co_u32_e32 v118, vcc, 0x6e00000, v136
	v_or_b32_sdwa v117, v117, v119 dst_sel:DWORD dst_unused:UNUSED_PAD src0_sel:DWORD src1_sel:WORD_1
	s_nop 0
	v_addc_co_u32_e32 v119, vcc, 0, v137, vcc
	global_store_dwordx2 v[118:119], v[116:117], off offset:1024
	v_cndmask_b32_e64 v116, 0, 1, s[64:65]
	v_cmp_ne_u32_e64 s[2:3], 1, v116
	v_mov_b64_e32 v[118:119], v[6:7]
	s_andn2_b64 vcc, exec, s[64:65]
	v_mov_b64_e32 v[116:117], v[4:5]
	s_cbranch_vccnz .LBB0_978
	global_load_dwordx4 v[116:119], v[130:131], off offset:64 nt
; __device__ __forceinline__ unsigned pk2(float lo, float hi) { return f2bf(lo) | (f2bf(hi) << 16); }
; __device__ __forceinline__ void ret_out_phase(const bf16* P1, const bf16* KVT, const bf16* ST, const float* retg, bf16* Y, LAS unsigned char* lds, int bid, int G, int tid, int wave, int lane) {
;     ...
; #pragma unroll
;         for (int te = 0; te < 8; ++te) {
;             const v2u gw2 = gq[te]; const f32x4 g4 = hfix ? g4h[te] : *(const f32x4*)(gg + 16 * te);
;             float gv[4] = {bflo(gw2.x), bfhi(gw2.x), bflo(gw2.y), bfhi(gw2.y)}; float y[4];
; #pragma unroll
;             for (int r = 0; r < 4; ++r) { const float sl = gv[r] / (1.f + __expf(-gv[r])); y[r] = (o[te][r] - mean) * rstd * g4[r] * sl; }
;             v2u ov; ov.x = pk2(y[0], y[1]); ov.y = pk2(y[2], y[3]);
;             *(v2u*)(yrow + 16 * te) = ov;
.LBB0_978:
	s_mov_b64 s[0:1], 0x6e00400
	v_mov_b32_e32 v133, v132
	v_mov_b32_e32 v123, v114
	v_mov_b32_e32 v114, v113
	v_and_b32_e32 v141, 0xffff0000, v214
	v_lshl_add_u64 v[120:121], v[136:137], 0, s[0:1]
	v_mov_b32_e32 v122, v112
	v_pk_add_f32 v[112:113], v[114:115], v[132:133] neg_lo:[0,1] neg_hi:[0,1]
	v_lshlrev_b32_e32 v137, 16, v215
	v_lshlrev_b32_e32 v138, 16, v214
	v_mul_f32_e32 v115, 0xbfb8aa3b, v141
	v_mul_f32_e32 v114, 0xbfb8aa3b, v138
	v_exp_f32_e32 v136, v115
	v_mul_f32_e32 v115, 0xbfb8aa3b, v137
	v_exp_f32_e32 v114, v114
	v_exp_f32_e32 v115, v115
	v_and_b32_e32 v140, 0xffff0000, v215
	v_mov_b32_e32 v125, v124
	v_pk_add_f32 v[122:123], v[122:123], v[132:133] neg_lo:[0,1] neg_hi:[0,1]
	v_pk_add_f32 v[114:115], v[114:115], 1.0 op_sel_hi:[1,0]
	v_pk_mul_f32 v[122:123], v[122:123], v[124:125]
	v_div_scale_f32 v139, s[0:1], v115, v115, v137
	v_rcp_f32_e32 v142, v139
	v_pk_mul_f32 v[112:113], v[112:113], v[124:125]
	v_fma_f32 v143, -v139, v142, 1.0
	v_fmac_f32_e32 v142, v143, v142
	v_div_scale_f32 v143, vcc, v137, v115, v137
	v_mul_f32_e32 v146, v143, v142
	v_fma_f32 v147, -v139, v146, v143
	v_fmac_f32_e32 v146, v147, v142
	v_fma_f32 v139, -v139, v146, v143
	v_div_fmas_f32 v139, v139, v142, v146
	v_div_fixup_f32 v115, v139, v115, v137
	v_div_scale_f32 v137, s[0:1], v114, v114, v138
	v_rcp_f32_e32 v139, v137
	s_nop 0
	v_fma_f32 v142, -v137, v139, 1.0
	v_fmac_f32_e32 v139, v142, v139
	v_div_scale_f32 v142, vcc, v138, v114, v138
	v_mul_f32_e32 v143, v142, v139
	v_fma_f32 v146, -v137, v143, v142
	v_fmac_f32_e32 v143, v146, v139
	v_fma_f32 v137, -v137, v143, v142
	v_div_fmas_f32 v137, v137, v139, v143
	v_div_fixup_f32 v114, v137, v114, v138
	s_waitcnt vmcnt(0)
	v_mov_b32_e32 v138, v116
	v_mul_f32_e32 v116, 0xbfb8aa3b, v140
	v_exp_f32_e32 v137, v116
	v_mov_b32_e32 v139, v118
	v_pk_mul_f32 v[122:123], v[122:123], v[138:139]
	s_nop 0
	v_pk_mul_f32 v[114:115], v[114:115], v[122:123]
	v_pk_add_f32 v[122:123], v[136:137], 1.0 op_sel_hi:[1,0]
	s_nop 0
	v_div_scale_f32 v116, s[0:1], v123, v123, v140
	v_rcp_f32_e32 v118, v116
	s_nop 0
	v_fma_f32 v136, -v116, v118, 1.0
	v_fmac_f32_e32 v118, v136, v118
	v_div_scale_f32 v136, vcc, v140, v123, v140
	v_mul_f32_e32 v137, v136, v118
	v_fma_f32 v138, -v116, v137, v136
	v_fmac_f32_e32 v137, v138, v118
	v_fma_f32 v116, -v116, v137, v136
	v_div_fmas_f32 v116, v116, v118, v137
	v_div_fixup_f32 v123, v116, v123, v140
	v_div_scale_f32 v116, s[0:1], v122, v122, v141
	v_rcp_f32_e32 v118, v116
	s_nop 0
	v_fma_f32 v136, -v116, v118, 1.0
	v_fmac_f32_e32 v118, v136, v118
	v_div_scale_f32 v136, vcc, v141, v122, v141
	v_mul_f32_e32 v137, v136, v118
	v_fma_f32 v138, -v116, v137, v136
	v_fmac_f32_e32 v137, v138, v118
	v_fma_f32 v116, -v116, v137, v136
	v_div_fmas_f32 v116, v116, v118, v137
	v_mov_b32_e32 v118, v117
	v_div_fixup_f32 v122, v116, v122, v141
	v_pk_mul_f32 v[112:113], v[112:113], v[118:119]
	v_and_b32_sdwa v116, v115, v220 dst_sel:DWORD dst_unused:UNUSED_PAD src0_sel:WORD_1 src1_sel:DWORD
	v_pk_mul_f32 v[112:113], v[122:123], v[112:113]
	v_and_b32_sdwa v117, v114, v220 dst_sel:DWORD dst_unused:UNUSED_PAD src0_sel:WORD_1 src1_sel:DWORD
	v_add3_u32 v114, v114, v117, s59
	v_add3_u32 v115, v115, v116, s59
	v_and_b32_sdwa v116, v113, v220 dst_sel:DWORD dst_unused:UNUSED_PAD src0_sel:WORD_1 src1_sel:DWORD
	v_and_b32_sdwa v117, v112, v220 dst_sel:DWORD dst_unused:UNUSED_PAD src0_sel:WORD_1 src1_sel:DWORD
	v_add3_u32 v113, v113, v116, s59
	v_add3_u32 v112, v112, v117, s59
	v_and_b32_e32 v113, 0xffff0000, v113
	v_and_b32_e32 v112, 0xffff0000, v112
	v_or_b32_sdwa v113, v113, v115 dst_sel:DWORD dst_unused:UNUSED_PAD src0_sel:DWORD src1_sel:WORD_1
	v_or_b32_sdwa v112, v112, v114 dst_sel:DWORD dst_unused:UNUSED_PAD src0_sel:DWORD src1_sel:WORD_1
	global_store_dwordx2 v[120:121], v[112:113], off offset:32
	v_mov_b64_e32 v[114:115], v[10:11]
	s_and_b64 vcc, exec, s[2:3]
	v_mov_b64_e32 v[112:113], v[8:9]
	s_cbranch_vccnz .LBB0_980
	global_load_dwordx4 v[112:115], v[130:131], off offset:128 nt
.LBB0_980:
	v_mov_b32_e32 v117, v110
	v_mov_b32_e32 v110, v109
	v_and_b32_e32 v137, 0xffff0000, v212
	v_mov_b32_e32 v116, v108
	v_pk_add_f32 v[108:109], v[110:111], v[132:133] neg_lo:[0,1] neg_hi:[0,1]
	v_lshlrev_b32_e32 v119, 16, v213
	v_lshlrev_b32_e32 v122, 16, v212
	v_mul_f32_e32 v111, 0xbfb8aa3b, v137
	v_mul_f32_e32 v110, 0xbfb8aa3b, v122
	v_exp_f32_e32 v118, v111
	v_mul_f32_e32 v111, 0xbfb8aa3b, v119
	v_exp_f32_e32 v110, v110
	v_exp_f32_e32 v111, v111
	v_and_b32_e32 v136, 0xffff0000, v213
	v_pk_add_f32 v[116:117], v[116:117], v[132:133] neg_lo:[0,1] neg_hi:[0,1]
	v_pk_mul_f32 v[108:109], v[108:109], v[124:125]
	v_pk_add_f32 v[110:111], v[110:111], 1.0 op_sel_hi:[1,0]
	v_pk_mul_f32 v[116:117], v[116:117], v[124:125]
	v_div_scale_f32 v123, s[0:1], v111, v111, v119
	v_rcp_f32_e32 v138, v123
	s_nop 0
	v_fma_f32 v139, -v123, v138, 1.0
	v_fmac_f32_e32 v138, v139, v138
	v_div_scale_f32 v139, vcc, v119, v111, v119
	v_mul_f32_e32 v140, v139, v138
	v_fma_f32 v141, -v123, v140, v139
	v_fmac_f32_e32 v140, v141, v138
	v_fma_f32 v123, -v123, v140, v139
	v_div_fmas_f32 v123, v123, v138, v140
	v_div_fixup_f32 v111, v123, v111, v119
	v_div_scale_f32 v119, s[0:1], v110, v110, v122
	v_rcp_f32_e32 v123, v119
	s_nop 0
	v_fma_f32 v138, -v119, v123, 1.0
	v_fmac_f32_e32 v123, v138, v123
	v_div_scale_f32 v138, vcc, v122, v110, v122
	v_mul_f32_e32 v139, v138, v123
	v_fma_f32 v140, -v119, v139, v138
	v_fmac_f32_e32 v139, v140, v123
	v_fma_f32 v119, -v119, v139, v138
	v_div_fmas_f32 v119, v119, v123, v139
	v_div_fixup_f32 v110, v119, v110, v122
	s_waitcnt vmcnt(0)
; __device__ __forceinline__ unsigned pk2(float lo, float hi) { return f2bf(lo) | (f2bf(hi) << 16); }
; __device__ __forceinline__ void ret_out_phase(const bf16* P1, const bf16* KVT, const bf16* ST, const float* retg, bf16* Y, LAS unsigned char* lds, int bid, int G, int tid, int wave, int lane) {
;     ...
; #pragma unroll
;         for (int te = 0; te < 8; ++te) {
;             const v2u gw2 = gq[te]; const f32x4 g4 = hfix ? g4h[te] : *(const f32x4*)(gg + 16 * te);
;             float gv[4] = {bflo(gw2.x), bfhi(gw2.x), bflo(gw2.y), bfhi(gw2.y)}; float y[4];
; #pragma unroll
;             for (int r = 0; r < 4; ++r) { const float sl = gv[r] / (1.f + __expf(-gv[r])); y[r] = (o[te][r] - mean) * rstd * g4[r] * sl; }
;             v2u ov; ov.x = pk2(y[0], y[1]); ov.y = pk2(y[2], y[3]);
;             *(v2u*)(yrow + 16 * te) = ov;
	v_mov_b32_e32 v122, v112
	v_mul_f32_e32 v112, 0xbfb8aa3b, v136
	v_exp_f32_e32 v119, v112
	v_mov_b32_e32 v123, v114
	v_pk_mul_f32 v[116:117], v[116:117], v[122:123]
	s_nop 0
	v_pk_mul_f32 v[110:111], v[110:111], v[116:117]
	v_pk_add_f32 v[116:117], v[118:119], 1.0 op_sel_hi:[1,0]
	s_nop 0
	v_div_scale_f32 v112, s[0:1], v117, v117, v136
	v_rcp_f32_e32 v114, v112
	s_nop 0
	v_fma_f32 v118, -v112, v114, 1.0
	v_fmac_f32_e32 v114, v118, v114
	v_div_scale_f32 v118, vcc, v136, v117, v136
	v_mul_f32_e32 v119, v118, v114
	v_fma_f32 v122, -v112, v119, v118
	v_fmac_f32_e32 v119, v122, v114
	v_fma_f32 v112, -v112, v119, v118
	v_div_fmas_f32 v112, v112, v114, v119
	v_div_fixup_f32 v117, v112, v117, v136
	v_div_scale_f32 v112, s[0:1], v116, v116, v137
	v_rcp_f32_e32 v114, v112
	s_nop 0
	v_fma_f32 v118, -v112, v114, 1.0
	v_fmac_f32_e32 v114, v118, v114
	v_div_scale_f32 v118, vcc, v137, v116, v137
	v_mul_f32_e32 v119, v118, v114
	v_fma_f32 v122, -v112, v119, v118
	v_fmac_f32_e32 v119, v122, v114
	v_fma_f32 v112, -v112, v119, v118
	v_div_fmas_f32 v112, v112, v114, v119
	v_mov_b32_e32 v114, v113
	v_div_fixup_f32 v116, v112, v116, v137
	v_pk_mul_f32 v[108:109], v[108:109], v[114:115]
	v_and_b32_sdwa v112, v111, v220 dst_sel:DWORD dst_unused:UNUSED_PAD src0_sel:WORD_1 src1_sel:DWORD
	v_pk_mul_f32 v[108:109], v[116:117], v[108:109]
	v_and_b32_sdwa v113, v110, v220 dst_sel:DWORD dst_unused:UNUSED_PAD src0_sel:WORD_1 src1_sel:DWORD
	v_add3_u32 v110, v110, v113, s59
	v_add3_u32 v111, v111, v112, s59
	v_and_b32_sdwa v112, v109, v220 dst_sel:DWORD dst_unused:UNUSED_PAD src0_sel:WORD_1 src1_sel:DWORD
	v_and_b32_sdwa v113, v108, v220 dst_sel:DWORD dst_unused:UNUSED_PAD src0_sel:WORD_1 src1_sel:DWORD
	v_add3_u32 v109, v109, v112, s59
	v_add3_u32 v108, v108, v113, s59
	v_and_b32_e32 v109, 0xffff0000, v109
	v_and_b32_e32 v108, 0xffff0000, v108
	v_or_b32_sdwa v109, v109, v111 dst_sel:DWORD dst_unused:UNUSED_PAD src0_sel:DWORD src1_sel:WORD_1
	v_or_b32_sdwa v108, v108, v110 dst_sel:DWORD dst_unused:UNUSED_PAD src0_sel:DWORD src1_sel:WORD_1
	global_store_dwordx2 v[120:121], v[108:109], off offset:64
	v_mov_b64_e32 v[110:111], v[14:15]
	s_and_b64 vcc, exec, s[2:3]
	v_mov_b64_e32 v[108:109], v[12:13]
	s_cbranch_vccnz .LBB0_982
	global_load_dwordx4 v[108:111], v[130:131], off offset:192 nt
.LBB0_982:
	v_mov_b32_e32 v113, v106
	v_mov_b32_e32 v106, v105
	v_and_b32_e32 v119, 0xffff0000, v210
	v_mov_b32_e32 v112, v104
	v_pk_add_f32 v[104:105], v[106:107], v[132:133] neg_lo:[0,1] neg_hi:[0,1]
	v_lshlrev_b32_e32 v115, 16, v211
	v_lshlrev_b32_e32 v116, 16, v210
	v_mul_f32_e32 v107, 0xbfb8aa3b, v119
	v_mul_f32_e32 v106, 0xbfb8aa3b, v116
	v_exp_f32_e32 v114, v107
	v_mul_f32_e32 v107, 0xbfb8aa3b, v115
	v_exp_f32_e32 v106, v106
	v_exp_f32_e32 v107, v107
	v_and_b32_e32 v118, 0xffff0000, v211
	v_pk_add_f32 v[112:113], v[112:113], v[132:133] neg_lo:[0,1] neg_hi:[0,1]
	v_pk_mul_f32 v[104:105], v[104:105], v[124:125]
	v_pk_add_f32 v[106:107], v[106:107], 1.0 op_sel_hi:[1,0]
	v_pk_mul_f32 v[112:113], v[112:113], v[124:125]
	v_div_scale_f32 v117, s[0:1], v107, v107, v115
	v_rcp_f32_e32 v122, v117
	s_nop 0
	v_fma_f32 v123, -v117, v122, 1.0
	v_fmac_f32_e32 v122, v123, v122
	v_div_scale_f32 v123, vcc, v115, v107, v115
	v_mul_f32_e32 v136, v123, v122
	v_fma_f32 v137, -v117, v136, v123
	v_fmac_f32_e32 v136, v137, v122
	v_fma_f32 v117, -v117, v136, v123
	v_div_fmas_f32 v117, v117, v122, v136
	v_div_fixup_f32 v107, v117, v107, v115
	v_div_scale_f32 v115, s[0:1], v106, v106, v116
	v_rcp_f32_e32 v117, v115
	s_nop 0
	v_fma_f32 v122, -v115, v117, 1.0
	v_fmac_f32_e32 v117, v122, v117
	v_div_scale_f32 v122, vcc, v116, v106, v116
	v_mul_f32_e32 v123, v122, v117
	v_fma_f32 v136, -v115, v123, v122
	v_fmac_f32_e32 v123, v136, v117
	v_fma_f32 v115, -v115, v123, v122
	v_div_fmas_f32 v115, v115, v117, v123
	v_div_fixup_f32 v106, v115, v106, v116
	s_waitcnt vmcnt(0)
	v_mov_b32_e32 v116, v108
	v_mul_f32_e32 v108, 0xbfb8aa3b, v118
	v_exp_f32_e32 v115, v108
	v_mov_b32_e32 v117, v110
	v_pk_mul_f32 v[112:113], v[112:113], v[116:117]
	s_nop 0
	v_pk_mul_f32 v[106:107], v[106:107], v[112:113]
	v_pk_add_f32 v[112:113], v[114:115], 1.0 op_sel_hi:[1,0]
	s_nop 0
	v_div_scale_f32 v108, s[0:1], v113, v113, v118
	v_rcp_f32_e32 v110, v108
	s_nop 0
	v_fma_f32 v114, -v108, v110, 1.0
	v_fmac_f32_e32 v110, v114, v110
	v_div_scale_f32 v114, vcc, v118, v113, v118
	v_mul_f32_e32 v115, v114, v110
	v_fma_f32 v116, -v108, v115, v114
	v_fmac_f32_e32 v115, v116, v110
	v_fma_f32 v108, -v108, v115, v114
	v_div_fmas_f32 v108, v108, v110, v115
	v_div_fixup_f32 v113, v108, v113, v118
	v_div_scale_f32 v108, s[0:1], v112, v112, v119
	v_rcp_f32_e32 v110, v108
	s_nop 0
	v_fma_f32 v114, -v108, v110, 1.0
	v_fmac_f32_e32 v110, v114, v110
	v_div_scale_f32 v114, vcc, v119, v112, v119
	v_mul_f32_e32 v115, v114, v110
	v_fma_f32 v116, -v108, v115, v114
	v_fmac_f32_e32 v115, v116, v110
	v_fma_f32 v108, -v108, v115, v114
	v_div_fmas_f32 v108, v108, v110, v115
	v_mov_b32_e32 v110, v109
	v_div_fixup_f32 v112, v108, v112, v119
	v_pk_mul_f32 v[104:105], v[104:105], v[110:111]
	v_and_b32_sdwa v108, v107, v220 dst_sel:DWORD dst_unused:UNUSED_PAD src0_sel:WORD_1 src1_sel:DWORD
	v_pk_mul_f32 v[104:105], v[112:113], v[104:105]
	v_and_b32_sdwa v109, v106, v220 dst_sel:DWORD dst_unused:UNUSED_PAD src0_sel:WORD_1 src1_sel:DWORD
	v_add3_u32 v106, v106, v109, s59
	v_add3_u32 v107, v107, v108, s59
	v_and_b32_sdwa v108, v105, v220 dst_sel:DWORD dst_unused:UNUSED_PAD src0_sel:WORD_1 src1_sel:DWORD
	v_and_b32_sdwa v109, v104, v220 dst_sel:DWORD dst_unused:UNUSED_PAD src0_sel:WORD_1 src1_sel:DWORD
	v_add3_u32 v105, v105, v108, s59
	v_add3_u32 v104, v104, v109, s59
	v_and_b32_e32 v105, 0xffff0000, v105
	v_and_b32_e32 v104, 0xffff0000, v104
	v_or_b32_sdwa v105, v105, v107 dst_sel:DWORD dst_unused:UNUSED_PAD src0_sel:DWORD src1_sel:WORD_1
	v_or_b32_sdwa v104, v104, v106 dst_sel:DWORD dst_unused:UNUSED_PAD src0_sel:DWORD src1_sel:WORD_1
	global_store_dwordx2 v[120:121], v[104:105], off offset:96
	v_mov_b64_e32 v[106:107], v[18:19]
	s_and_b64 vcc, exec, s[2:3]
	v_mov_b64_e32 v[104:105], v[16:17]
	s_cbranch_vccnz .LBB0_984
	global_load_dwordx4 v[104:107], v[130:131], off offset:256 nt
; __device__ __forceinline__ unsigned pk2(float lo, float hi) { return f2bf(lo) | (f2bf(hi) << 16); }
; __device__ __forceinline__ void ret_out_phase(const bf16* P1, const bf16* KVT, const bf16* ST, const float* retg, bf16* Y, LAS unsigned char* lds, int bid, int G, int tid, int wave, int lane) {
;     ...
; #pragma unroll
;         for (int te = 0; te < 8; ++te) {
;             const v2u gw2 = gq[te]; const f32x4 g4 = hfix ? g4h[te] : *(const f32x4*)(gg + 16 * te);
;             float gv[4] = {bflo(gw2.x), bfhi(gw2.x), bflo(gw2.y), bfhi(gw2.y)}; float y[4];
; #pragma unroll
;             for (int r = 0; r < 4; ++r) { const float sl = gv[r] / (1.f + __expf(-gv[r])); y[r] = (o[te][r] - mean) * rstd * g4[r] * sl; }
;             v2u ov; ov.x = pk2(y[0], y[1]); ov.y = pk2(y[2], y[3]);
;             *(v2u*)(yrow + 16 * te) = ov;
.LBB0_984:
	v_and_b32_e32 v119, 0xffff0000, v208
	v_lshlrev_b32_e32 v115, 16, v209
	v_lshlrev_b32_e32 v116, 16, v208
	v_mul_f32_e32 v113, 0xbfb8aa3b, v119
	v_mul_f32_e32 v112, 0xbfb8aa3b, v116
	v_exp_f32_e32 v114, v113
	v_mul_f32_e32 v113, 0xbfb8aa3b, v115
	v_exp_f32_e32 v112, v112
	v_exp_f32_e32 v113, v113
	v_pk_add_f32 v[108:109], v[134:135], v[132:133] neg_lo:[0,1] neg_hi:[0,1]
	v_and_b32_e32 v118, 0xffff0000, v209
	v_pk_mul_f32 v[108:109], v[108:109], v[124:125]
	v_pk_add_f32 v[112:113], v[112:113], 1.0 op_sel_hi:[1,0]
	v_pk_add_f32 v[110:111], v[144:145], v[132:133] neg_lo:[0,1] neg_hi:[0,1]
	v_div_scale_f32 v117, s[0:1], v113, v113, v115
	v_rcp_f32_e32 v122, v117
	v_pk_mul_f32 v[110:111], v[110:111], v[124:125]
	v_fma_f32 v123, -v117, v122, 1.0
	v_fmac_f32_e32 v122, v123, v122
	v_div_scale_f32 v123, vcc, v115, v113, v115
	v_mul_f32_e32 v134, v123, v122
	v_fma_f32 v135, -v117, v134, v123
	v_fmac_f32_e32 v134, v135, v122
	v_fma_f32 v117, -v117, v134, v123
	v_div_fmas_f32 v117, v117, v122, v134
	v_div_fixup_f32 v113, v117, v113, v115
	v_div_scale_f32 v115, s[0:1], v112, v112, v116
	v_rcp_f32_e32 v117, v115
	s_nop 0
	v_fma_f32 v122, -v115, v117, 1.0
	v_fmac_f32_e32 v117, v122, v117
	v_div_scale_f32 v122, vcc, v116, v112, v116
	v_mul_f32_e32 v123, v122, v117
	v_fma_f32 v134, -v115, v123, v122
	v_fmac_f32_e32 v123, v134, v117
	v_fma_f32 v115, -v115, v123, v122
	v_div_fmas_f32 v115, v115, v117, v123
	v_div_fixup_f32 v112, v115, v112, v116
	s_waitcnt vmcnt(0)
	v_mov_b32_e32 v116, v104
	v_mul_f32_e32 v104, 0xbfb8aa3b, v118
	v_exp_f32_e32 v115, v104
	v_mov_b32_e32 v117, v106
	v_pk_mul_f32 v[108:109], v[108:109], v[116:117]
	s_nop 0
	v_pk_mul_f32 v[108:109], v[112:113], v[108:109]
	v_pk_add_f32 v[112:113], v[114:115], 1.0 op_sel_hi:[1,0]
	s_nop 0
	v_div_scale_f32 v104, s[0:1], v113, v113, v118
	v_rcp_f32_e32 v106, v104
	s_nop 0
	v_fma_f32 v114, -v104, v106, 1.0
	v_fmac_f32_e32 v106, v114, v106
	v_div_scale_f32 v114, vcc, v118, v113, v118
	v_mul_f32_e32 v115, v114, v106
	v_fma_f32 v116, -v104, v115, v114
	v_fmac_f32_e32 v115, v116, v106
	v_fma_f32 v104, -v104, v115, v114
	v_div_fmas_f32 v104, v104, v106, v115
	v_div_fixup_f32 v113, v104, v113, v118
	v_div_scale_f32 v104, s[0:1], v112, v112, v119
	v_rcp_f32_e32 v106, v104
	s_nop 0
	v_fma_f32 v114, -v104, v106, 1.0
	v_fmac_f32_e32 v106, v114, v106
	v_div_scale_f32 v114, vcc, v119, v112, v119
	v_mul_f32_e32 v115, v114, v106
	v_fma_f32 v116, -v104, v115, v114
	v_fmac_f32_e32 v115, v116, v106
	v_fma_f32 v104, -v104, v115, v114
	v_div_fmas_f32 v104, v104, v106, v115
	v_mov_b32_e32 v106, v105
	v_div_fixup_f32 v112, v104, v112, v119
	v_pk_mul_f32 v[104:105], v[110:111], v[106:107]
	v_and_b32_sdwa v106, v109, v220 dst_sel:DWORD dst_unused:UNUSED_PAD src0_sel:WORD_1 src1_sel:DWORD
	v_pk_mul_f32 v[104:105], v[112:113], v[104:105]
	v_and_b32_sdwa v107, v108, v220 dst_sel:DWORD dst_unused:UNUSED_PAD src0_sel:WORD_1 src1_sel:DWORD
	v_add3_u32 v107, v108, v107, s59
	v_add3_u32 v106, v109, v106, s59
	v_and_b32_sdwa v108, v105, v220 dst_sel:DWORD dst_unused:UNUSED_PAD src0_sel:WORD_1 src1_sel:DWORD
	v_and_b32_sdwa v109, v104, v220 dst_sel:DWORD dst_unused:UNUSED_PAD src0_sel:WORD_1 src1_sel:DWORD
	v_add3_u32 v105, v105, v108, s59
	v_add3_u32 v104, v104, v109, s59
	v_and_b32_e32 v105, 0xffff0000, v105
	v_and_b32_e32 v104, 0xffff0000, v104
	v_or_b32_sdwa v105, v105, v106 dst_sel:DWORD dst_unused:UNUSED_PAD src0_sel:DWORD src1_sel:WORD_1
	v_or_b32_sdwa v104, v104, v107 dst_sel:DWORD dst_unused:UNUSED_PAD src0_sel:DWORD src1_sel:WORD_1
	global_store_dwordx2 v[120:121], v[104:105], off offset:128
	v_mov_b64_e32 v[106:107], v[22:23]
	s_and_b64 vcc, exec, s[2:3]
	v_mov_b64_e32 v[104:105], v[20:21]
	s_cbranch_vccnz .LBB0_986
	global_load_dwordx4 v[104:107], v[130:131], off offset:320 nt
.LBB0_986:
	v_mov_b32_e32 v109, v102
	v_mov_b32_e32 v102, v101
	v_and_b32_e32 v115, 0xffff0000, v206
	v_mov_b32_e32 v108, v100
	v_pk_add_f32 v[100:101], v[102:103], v[132:133] neg_lo:[0,1] neg_hi:[0,1]
	v_lshlrev_b32_e32 v111, 16, v207
	v_lshlrev_b32_e32 v112, 16, v206
	v_mul_f32_e32 v103, 0xbfb8aa3b, v115
	v_mul_f32_e32 v102, 0xbfb8aa3b, v112
	v_exp_f32_e32 v110, v103
	v_mul_f32_e32 v103, 0xbfb8aa3b, v111
	v_exp_f32_e32 v102, v102
	v_exp_f32_e32 v103, v103
	v_and_b32_e32 v114, 0xffff0000, v207
	v_pk_add_f32 v[108:109], v[108:109], v[132:133] neg_lo:[0,1] neg_hi:[0,1]
	v_pk_mul_f32 v[100:101], v[100:101], v[124:125]
	v_pk_add_f32 v[102:103], v[102:103], 1.0 op_sel_hi:[1,0]
	v_pk_mul_f32 v[108:109], v[108:109], v[124:125]
	v_div_scale_f32 v113, s[0:1], v103, v103, v111
	v_rcp_f32_e32 v116, v113
	s_nop 0
	v_fma_f32 v117, -v113, v116, 1.0
	v_fmac_f32_e32 v116, v117, v116
	v_div_scale_f32 v117, vcc, v111, v103, v111
	v_mul_f32_e32 v118, v117, v116
	v_fma_f32 v119, -v113, v118, v117
	v_fmac_f32_e32 v118, v119, v116
	v_fma_f32 v113, -v113, v118, v117
	v_div_fmas_f32 v113, v113, v116, v118
	v_div_fixup_f32 v103, v113, v103, v111
	v_div_scale_f32 v111, s[0:1], v102, v102, v112
	v_rcp_f32_e32 v113, v111
	s_nop 0
	v_fma_f32 v116, -v111, v113, 1.0
	v_fmac_f32_e32 v113, v116, v113
	v_div_scale_f32 v116, vcc, v112, v102, v112
	v_mul_f32_e32 v117, v116, v113
	v_fma_f32 v118, -v111, v117, v116
	v_fmac_f32_e32 v117, v118, v113
	v_fma_f32 v111, -v111, v117, v116
	v_div_fmas_f32 v111, v111, v113, v117
	v_div_fixup_f32 v102, v111, v102, v112
	s_waitcnt vmcnt(0)
; __device__ __forceinline__ unsigned pk2(float lo, float hi) { return f2bf(lo) | (f2bf(hi) << 16); }
; __device__ __forceinline__ void ret_out_phase(const bf16* P1, const bf16* KVT, const bf16* ST, const float* retg, bf16* Y, LAS unsigned char* lds, int bid, int G, int tid, int wave, int lane) {
;     ...
; #pragma unroll
;         for (int te = 0; te < 8; ++te) {
;             const v2u gw2 = gq[te]; const f32x4 g4 = hfix ? g4h[te] : *(const f32x4*)(gg + 16 * te);
;             float gv[4] = {bflo(gw2.x), bfhi(gw2.x), bflo(gw2.y), bfhi(gw2.y)}; float y[4];
; #pragma unroll
;             for (int r = 0; r < 4; ++r) { const float sl = gv[r] / (1.f + __expf(-gv[r])); y[r] = (o[te][r] - mean) * rstd * g4[r] * sl; }
;             v2u ov; ov.x = pk2(y[0], y[1]); ov.y = pk2(y[2], y[3]);
;             *(v2u*)(yrow + 16 * te) = ov;
	v_mov_b32_e32 v112, v104
	v_mul_f32_e32 v104, 0xbfb8aa3b, v114
	v_exp_f32_e32 v111, v104
	v_mov_b32_e32 v113, v106
	v_pk_mul_f32 v[108:109], v[108:109], v[112:113]
	s_nop 0
	v_pk_mul_f32 v[102:103], v[102:103], v[108:109]
	v_pk_add_f32 v[108:109], v[110:111], 1.0 op_sel_hi:[1,0]
	s_nop 0
	v_div_scale_f32 v104, s[0:1], v109, v109, v114
	v_rcp_f32_e32 v106, v104
	s_nop 0
	v_fma_f32 v110, -v104, v106, 1.0
	v_fmac_f32_e32 v106, v110, v106
	v_div_scale_f32 v110, vcc, v114, v109, v114
	v_mul_f32_e32 v111, v110, v106
	v_fma_f32 v112, -v104, v111, v110
	v_fmac_f32_e32 v111, v112, v106
	v_fma_f32 v104, -v104, v111, v110
	v_div_fmas_f32 v104, v104, v106, v111
	v_div_fixup_f32 v109, v104, v109, v114
	v_div_scale_f32 v104, s[0:1], v108, v108, v115
	v_rcp_f32_e32 v106, v104
	s_nop 0
	v_fma_f32 v110, -v104, v106, 1.0
	v_fmac_f32_e32 v106, v110, v106
	v_div_scale_f32 v110, vcc, v115, v108, v115
	v_mul_f32_e32 v111, v110, v106
	v_fma_f32 v112, -v104, v111, v110
	v_fmac_f32_e32 v111, v112, v106
	v_fma_f32 v104, -v104, v111, v110
	v_div_fmas_f32 v104, v104, v106, v111
	v_mov_b32_e32 v106, v105
	v_div_fixup_f32 v108, v104, v108, v115
	v_pk_mul_f32 v[100:101], v[100:101], v[106:107]
	v_and_b32_sdwa v104, v103, v220 dst_sel:DWORD dst_unused:UNUSED_PAD src0_sel:WORD_1 src1_sel:DWORD
	v_pk_mul_f32 v[100:101], v[108:109], v[100:101]
	v_and_b32_sdwa v105, v102, v220 dst_sel:DWORD dst_unused:UNUSED_PAD src0_sel:WORD_1 src1_sel:DWORD
	v_add3_u32 v102, v102, v105, s59
	v_add3_u32 v103, v103, v104, s59
	v_and_b32_sdwa v104, v101, v220 dst_sel:DWORD dst_unused:UNUSED_PAD src0_sel:WORD_1 src1_sel:DWORD
	v_and_b32_sdwa v105, v100, v220 dst_sel:DWORD dst_unused:UNUSED_PAD src0_sel:WORD_1 src1_sel:DWORD
	v_add3_u32 v101, v101, v104, s59
	v_add3_u32 v100, v100, v105, s59
	v_and_b32_e32 v101, 0xffff0000, v101
	v_and_b32_e32 v100, 0xffff0000, v100
	v_or_b32_sdwa v101, v101, v103 dst_sel:DWORD dst_unused:UNUSED_PAD src0_sel:DWORD src1_sel:WORD_1
	v_or_b32_sdwa v100, v100, v102 dst_sel:DWORD dst_unused:UNUSED_PAD src0_sel:DWORD src1_sel:WORD_1
	global_store_dwordx2 v[120:121], v[100:101], off offset:160
	v_mov_b64_e32 v[102:103], v[26:27]
	s_and_b64 vcc, exec, s[2:3]
	v_mov_b64_e32 v[100:101], v[24:25]
	s_cbranch_vccnz .LBB0_988
	global_load_dwordx4 v[100:103], v[130:131], off offset:384 nt
.LBB0_988:
	v_mov_b32_e32 v105, v98
	v_mov_b32_e32 v98, v97
	v_and_b32_e32 v111, 0xffff0000, v204
	v_mov_b32_e32 v104, v96
	v_pk_add_f32 v[96:97], v[98:99], v[132:133] neg_lo:[0,1] neg_hi:[0,1]
	v_lshlrev_b32_e32 v107, 16, v205
	v_lshlrev_b32_e32 v108, 16, v204
	v_mul_f32_e32 v99, 0xbfb8aa3b, v111
	v_mul_f32_e32 v98, 0xbfb8aa3b, v108
	v_exp_f32_e32 v106, v99
	v_mul_f32_e32 v99, 0xbfb8aa3b, v107
	v_exp_f32_e32 v98, v98
	v_exp_f32_e32 v99, v99
	v_and_b32_e32 v110, 0xffff0000, v205
	v_pk_add_f32 v[104:105], v[104:105], v[132:133] neg_lo:[0,1] neg_hi:[0,1]
	v_pk_mul_f32 v[96:97], v[96:97], v[124:125]
	v_pk_add_f32 v[98:99], v[98:99], 1.0 op_sel_hi:[1,0]
	v_pk_mul_f32 v[104:105], v[104:105], v[124:125]
	v_div_scale_f32 v109, s[0:1], v99, v99, v107
	v_rcp_f32_e32 v112, v109
	s_nop 0
	v_fma_f32 v113, -v109, v112, 1.0
	v_fmac_f32_e32 v112, v113, v112
	v_div_scale_f32 v113, vcc, v107, v99, v107
	v_mul_f32_e32 v114, v113, v112
	v_fma_f32 v115, -v109, v114, v113
	v_fmac_f32_e32 v114, v115, v112
	v_fma_f32 v109, -v109, v114, v113
	v_div_fmas_f32 v109, v109, v112, v114
	v_div_fixup_f32 v99, v109, v99, v107
	v_div_scale_f32 v107, s[0:1], v98, v98, v108
	v_rcp_f32_e32 v109, v107
	s_nop 0
	v_fma_f32 v112, -v107, v109, 1.0
	v_fmac_f32_e32 v109, v112, v109
	v_div_scale_f32 v112, vcc, v108, v98, v108
	v_mul_f32_e32 v113, v112, v109
	v_fma_f32 v114, -v107, v113, v112
	v_fmac_f32_e32 v113, v114, v109
	v_fma_f32 v107, -v107, v113, v112
	v_div_fmas_f32 v107, v107, v109, v113
	v_div_fixup_f32 v98, v107, v98, v108
	s_waitcnt vmcnt(0)
	v_mov_b32_e32 v108, v100
	v_mul_f32_e32 v100, 0xbfb8aa3b, v110
	v_exp_f32_e32 v107, v100
	v_mov_b32_e32 v109, v102
	v_pk_mul_f32 v[104:105], v[104:105], v[108:109]
	s_nop 0
	v_pk_mul_f32 v[98:99], v[98:99], v[104:105]
	v_pk_add_f32 v[104:105], v[106:107], 1.0 op_sel_hi:[1,0]
	s_nop 0
	v_div_scale_f32 v100, s[0:1], v105, v105, v110
	v_rcp_f32_e32 v102, v100
	s_nop 0
	v_fma_f32 v106, -v100, v102, 1.0
	v_fmac_f32_e32 v102, v106, v102
	v_div_scale_f32 v106, vcc, v110, v105, v110
	v_mul_f32_e32 v107, v106, v102
	v_fma_f32 v108, -v100, v107, v106
	v_fmac_f32_e32 v107, v108, v102
	v_fma_f32 v100, -v100, v107, v106
	v_div_fmas_f32 v100, v100, v102, v107
	v_div_fixup_f32 v105, v100, v105, v110
	v_div_scale_f32 v100, s[0:1], v104, v104, v111
	v_rcp_f32_e32 v102, v100
	s_nop 0
	v_fma_f32 v106, -v100, v102, 1.0
	v_fmac_f32_e32 v102, v106, v102
	v_div_scale_f32 v106, vcc, v111, v104, v111
	v_mul_f32_e32 v107, v106, v102
	v_fma_f32 v108, -v100, v107, v106
	v_fmac_f32_e32 v107, v108, v102
	v_fma_f32 v100, -v100, v107, v106
	v_div_fmas_f32 v100, v100, v102, v107
	v_mov_b32_e32 v102, v101
	v_div_fixup_f32 v104, v100, v104, v111
	v_pk_mul_f32 v[96:97], v[96:97], v[102:103]
	v_and_b32_sdwa v100, v99, v220 dst_sel:DWORD dst_unused:UNUSED_PAD src0_sel:WORD_1 src1_sel:DWORD
	v_pk_mul_f32 v[96:97], v[104:105], v[96:97]
	v_and_b32_sdwa v101, v98, v220 dst_sel:DWORD dst_unused:UNUSED_PAD src0_sel:WORD_1 src1_sel:DWORD
	v_add3_u32 v98, v98, v101, s59
	v_add3_u32 v99, v99, v100, s59
	v_and_b32_sdwa v100, v97, v220 dst_sel:DWORD dst_unused:UNUSED_PAD src0_sel:WORD_1 src1_sel:DWORD
	v_and_b32_sdwa v101, v96, v220 dst_sel:DWORD dst_unused:UNUSED_PAD src0_sel:WORD_1 src1_sel:DWORD
	v_add3_u32 v97, v97, v100, s59
	v_add3_u32 v96, v96, v101, s59
	v_and_b32_e32 v97, 0xffff0000, v97
	v_and_b32_e32 v96, 0xffff0000, v96
	v_or_b32_sdwa v97, v97, v99 dst_sel:DWORD dst_unused:UNUSED_PAD src0_sel:DWORD src1_sel:WORD_1
	v_or_b32_sdwa v96, v96, v98 dst_sel:DWORD dst_unused:UNUSED_PAD src0_sel:DWORD src1_sel:WORD_1
	global_store_dwordx2 v[120:121], v[96:97], off offset:192
	v_mov_b64_e32 v[98:99], v[30:31]
	s_and_b64 vcc, exec, s[2:3]
	v_mov_b64_e32 v[96:97], v[28:29]
	s_cbranch_vccnz .LBB0_990
	global_load_dwordx4 v[96:99], v[130:131], off offset:448 nt
